# phase-0 adaLN GEMV: 64 serialized load-wait-fma steps replaced by 64 loads issued up front with counted vmcnt waits, double-buffered LDS sv reads
# speedup vs baseline: 1.0727x; 1.0163x over previous
.LBB0_9:
	v_readlane_b32 s4, v255, 7
	s_cmp_eq_u32 s4, 0
	v_add_co_u32_e64 v1, s[0:1], s27, 1
	s_cselect_b64 s[2:3], -1, 0
	s_and_b64 s[0:1], s[0:1], s[2:3]
	s_and_b64 s[0:1], s[0:1], exec
	v_readfirstlane_b32 s0, v1
	s_cselect_b32 s4, 1, s4
	s_cselect_b32 s27, -1, s0
	v_writelane_b32 v255, s4, 7
	s_cmp_gt_i32 s27, 17
	s_cbranch_scc0 .LBB0_10
	s_endpgm

.Latt_u_noS:
	s_add_i32 s49, s49, 1
	s_cmp_gt_u32 s49, s47
	s_cbranch_scc1 .LBB0_44
	s_barrier
	s_branch .Latt_u_loop
	s_nop 0
	s_nop 0
	s_nop 0
	s_nop 0
	s_nop 0
	s_nop 0
	s_nop 0
	s_nop 0
	s_nop 0
	s_nop 0
	s_nop 0
	s_nop 0
	s_nop 0
	s_nop 0
	s_nop 0
	s_nop 0
	s_nop 0
	s_nop 0
	s_nop 0
	s_nop 0
	s_nop 0
	s_nop 0
	s_nop 0
	s_nop 0
	s_nop 0
	s_nop 0
	s_nop 0
	s_nop 0
	s_nop 0
	s_nop 0
	s_nop 0
	s_nop 0
	s_nop 0
	s_nop 0
	s_nop 0
	s_nop 0
	s_nop 0
	s_nop 0
	s_nop 0
	s_nop 0
	s_nop 0
	s_nop 0
	s_nop 0
	s_nop 0
	s_nop 0
	s_nop 0
	s_nop 0
	s_nop 0
	s_nop 0
	s_nop 0
	s_nop 0
	s_nop 0
	s_nop 0
	s_nop 0
	s_nop 0
.LBB0_75:
	v_readlane_b32 s54, v255, 12
	s_mov_b64 s[8:9], 0
	v_readlane_b32 s55, v255, 13
	v_readlane_b32 s27, v255, 31

.LBB0_1569:
	v_subrev_u32_e32 v28, 30, v27
	v_mul_u32_u24_e32 v28, 0x6000, v28
	v_lshl_add_u32 v28, v4, 2, v28
	s_mov_b64 s[6:7], s[44:45]
	v_add_u32_e32 v29, 0x10800, v25
	global_load_dword v36, v28, s[6:7] nt
	s_add_u32 s6, s6, 0xc000
	s_addc_u32 s7, s7, 0
	global_load_dword v38, v28, s[6:7] nt
	s_add_u32 s6, s6, 0xc000
	s_addc_u32 s7, s7, 0
	global_load_dword v40, v28, s[6:7] nt
	s_add_u32 s6, s6, 0xc000
	s_addc_u32 s7, s7, 0
	global_load_dword v42, v28, s[6:7] nt
	s_add_u32 s6, s6, 0xc000
	s_addc_u32 s7, s7, 0
	global_load_dword v44, v28, s[6:7] nt
	s_add_u32 s6, s6, 0xc000
	s_addc_u32 s7, s7, 0
	global_load_dword v46, v28, s[6:7] nt
	s_add_u32 s6, s6, 0xc000
	s_addc_u32 s7, s7, 0
	global_load_dword v48, v28, s[6:7] nt
	s_add_u32 s6, s6, 0xc000
	s_addc_u32 s7, s7, 0
	global_load_dword v50, v28, s[6:7] nt
	s_add_u32 s6, s6, 0xc000
	s_addc_u32 s7, s7, 0
	global_load_dword v52, v28, s[6:7] nt
	s_add_u32 s6, s6, 0xc000
	s_addc_u32 s7, s7, 0
	global_load_dword v54, v28, s[6:7] nt
	s_add_u32 s6, s6, 0xc000
	s_addc_u32 s7, s7, 0
	global_load_dword v56, v28, s[6:7] nt
	s_add_u32 s6, s6, 0xc000
	s_addc_u32 s7, s7, 0
	global_load_dword v58, v28, s[6:7] nt
	s_add_u32 s6, s6, 0xc000
	s_addc_u32 s7, s7, 0
	global_load_dword v60, v28, s[6:7] nt
	s_add_u32 s6, s6, 0xc000
	s_addc_u32 s7, s7, 0
	global_load_dword v62, v28, s[6:7] nt
	s_add_u32 s6, s6, 0xc000
	s_addc_u32 s7, s7, 0
	global_load_dword v64, v28, s[6:7] nt
	s_add_u32 s6, s6, 0xc000
	s_addc_u32 s7, s7, 0
	global_load_dword v66, v28, s[6:7] nt
	s_add_u32 s6, s6, 0xc000
	s_addc_u32 s7, s7, 0
	global_load_dword v68, v28, s[6:7] nt
	s_add_u32 s6, s6, 0xc000
	s_addc_u32 s7, s7, 0
	global_load_dword v70, v28, s[6:7] nt
	s_add_u32 s6, s6, 0xc000
	s_addc_u32 s7, s7, 0
	global_load_dword v72, v28, s[6:7] nt
	s_add_u32 s6, s6, 0xc000
	s_addc_u32 s7, s7, 0
	global_load_dword v74, v28, s[6:7] nt
	s_add_u32 s6, s6, 0xc000
	s_addc_u32 s7, s7, 0
	global_load_dword v76, v28, s[6:7] nt
	s_add_u32 s6, s6, 0xc000
	s_addc_u32 s7, s7, 0
	global_load_dword v78, v28, s[6:7] nt
	s_add_u32 s6, s6, 0xc000
	s_addc_u32 s7, s7, 0
	global_load_dword v80, v28, s[6:7] nt
	s_add_u32 s6, s6, 0xc000
	s_addc_u32 s7, s7, 0
	global_load_dword v82, v28, s[6:7] nt
	s_add_u32 s6, s6, 0xc000
	s_addc_u32 s7, s7, 0
	global_load_dword v84, v28, s[6:7] nt
	s_add_u32 s6, s6, 0xc000
	s_addc_u32 s7, s7, 0
	global_load_dword v86, v28, s[6:7] nt
	s_add_u32 s6, s6, 0xc000
	s_addc_u32 s7, s7, 0
	global_load_dword v88, v28, s[6:7] nt
	s_add_u32 s6, s6, 0xc000
	s_addc_u32 s7, s7, 0
	global_load_dword v90, v28, s[6:7] nt
	s_add_u32 s6, s6, 0xc000
	s_addc_u32 s7, s7, 0
	global_load_dword v92, v28, s[6:7] nt
	s_add_u32 s6, s6, 0xc000
	s_addc_u32 s7, s7, 0
	global_load_dword v94, v28, s[6:7] nt
	s_add_u32 s6, s6, 0xc000
	s_addc_u32 s7, s7, 0
	global_load_dword v96, v28, s[6:7] nt
	s_add_u32 s6, s6, 0xc000
	s_addc_u32 s7, s7, 0
	global_load_dword v98, v28, s[6:7] nt
	s_add_u32 s6, s6, 0xc000
	s_addc_u32 s7, s7, 0
	global_load_dword v100, v28, s[6:7] nt
	s_add_u32 s6, s6, 0xc000
	s_addc_u32 s7, s7, 0
	global_load_dword v102, v28, s[6:7] nt
	s_add_u32 s6, s6, 0xc000
	s_addc_u32 s7, s7, 0
	global_load_dword v104, v28, s[6:7] nt
	s_add_u32 s6, s6, 0xc000
	s_addc_u32 s7, s7, 0
	global_load_dword v106, v28, s[6:7] nt
	s_add_u32 s6, s6, 0xc000
	s_addc_u32 s7, s7, 0
	global_load_dword v108, v28, s[6:7] nt
	s_add_u32 s6, s6, 0xc000
	s_addc_u32 s7, s7, 0
	global_load_dword v110, v28, s[6:7] nt
	s_add_u32 s6, s6, 0xc000
	s_addc_u32 s7, s7, 0
	global_load_dword v112, v28, s[6:7] nt
	s_add_u32 s6, s6, 0xc000
	s_addc_u32 s7, s7, 0
	global_load_dword v114, v28, s[6:7] nt
	s_add_u32 s6, s6, 0xc000
	s_addc_u32 s7, s7, 0
	global_load_dword v116, v28, s[6:7] nt
	s_add_u32 s6, s6, 0xc000
	s_addc_u32 s7, s7, 0
	global_load_dword v118, v28, s[6:7] nt
	s_add_u32 s6, s6, 0xc000
	s_addc_u32 s7, s7, 0
	global_load_dword v120, v28, s[6:7] nt
	s_add_u32 s6, s6, 0xc000
	s_addc_u32 s7, s7, 0
	global_load_dword v122, v28, s[6:7] nt
	s_add_u32 s6, s6, 0xc000
	s_addc_u32 s7, s7, 0
	global_load_dword v124, v28, s[6:7] nt
	s_add_u32 s6, s6, 0xc000
	s_addc_u32 s7, s7, 0
	global_load_dword v126, v28, s[6:7] nt
	s_add_u32 s6, s6, 0xc000
	s_addc_u32 s7, s7, 0
	global_load_dword v128, v28, s[6:7] nt
	s_add_u32 s6, s6, 0xc000
	s_addc_u32 s7, s7, 0
	global_load_dword v130, v28, s[6:7] nt
	s_add_u32 s6, s6, 0xc000
	s_addc_u32 s7, s7, 0
	global_load_dword v132, v28, s[6:7] nt
	s_add_u32 s6, s6, 0xc000
	s_addc_u32 s7, s7, 0
	global_load_dword v134, v28, s[6:7] nt
	s_add_u32 s6, s6, 0xc000
	s_addc_u32 s7, s7, 0
	global_load_dword v136, v28, s[6:7] nt
	s_add_u32 s6, s6, 0xc000
	s_addc_u32 s7, s7, 0
	global_load_dword v138, v28, s[6:7] nt
	s_add_u32 s6, s6, 0xc000
	s_addc_u32 s7, s7, 0
	global_load_dword v140, v28, s[6:7] nt
	s_add_u32 s6, s6, 0xc000
	s_addc_u32 s7, s7, 0
	global_load_dword v142, v28, s[6:7] nt
	s_add_u32 s6, s6, 0xc000
	s_addc_u32 s7, s7, 0
	global_load_dword v144, v28, s[6:7] nt
	s_add_u32 s6, s6, 0xc000
	s_addc_u32 s7, s7, 0
	global_load_dword v146, v28, s[6:7] nt
	s_add_u32 s6, s6, 0xc000
	s_addc_u32 s7, s7, 0
	global_load_dword v148, v28, s[6:7] nt
	s_add_u32 s6, s6, 0xc000
	s_addc_u32 s7, s7, 0
	global_load_dword v150, v28, s[6:7] nt
	s_add_u32 s6, s6, 0xc000
	s_addc_u32 s7, s7, 0
	global_load_dword v152, v28, s[6:7] nt
	s_add_u32 s6, s6, 0xc000
	s_addc_u32 s7, s7, 0
	global_load_dword v154, v28, s[6:7] nt
	s_add_u32 s6, s6, 0xc000
	s_addc_u32 s7, s7, 0
	global_load_dword v156, v28, s[6:7] nt
	s_add_u32 s6, s6, 0xc000
	s_addc_u32 s7, s7, 0
	global_load_dword v158, v28, s[6:7] nt
	s_add_u32 s6, s6, 0xc000
	s_addc_u32 s7, s7, 0
	global_load_dword v160, v28, s[6:7] nt
	s_add_u32 s6, s6, 0xc000
	s_addc_u32 s7, s7, 0
	global_load_dword v162, v28, s[6:7] nt
	ds_read_b128 v[166:169], v29 offset:0
	ds_read_b128 v[170:173], v29 offset:16
	ds_read_b128 v[174:177], v29 offset:32
	ds_read_b128 v[178:181], v29 offset:48
	ds_read_b128 v[182:185], v29 offset:128
	ds_read_b128 v[186:189], v29 offset:144
	ds_read_b128 v[190:193], v29 offset:160
	ds_read_b128 v[194:197], v29 offset:176
	s_waitcnt vmcnt(63) lgkmcnt(4)
	v_pk_fma_f32 v[22:23], v[36:37], v[166:167], v[22:23] op_sel_hi:[0,1,1]
	v_pk_fma_f32 v[20:21], v[36:37], v[168:169], v[20:21] op_sel_hi:[0,1,1]
	v_pk_fma_f32 v[18:19], v[36:37], v[170:171], v[18:19] op_sel_hi:[0,1,1]
	v_pk_fma_f32 v[16:17], v[36:37], v[172:173], v[16:17] op_sel_hi:[0,1,1]
	v_pk_fma_f32 v[14:15], v[36:37], v[174:175], v[14:15] op_sel_hi:[0,1,1]
	v_pk_fma_f32 v[12:13], v[36:37], v[176:177], v[12:13] op_sel_hi:[0,1,1]
	v_pk_fma_f32 v[10:11], v[36:37], v[178:179], v[10:11] op_sel_hi:[0,1,1]
	v_pk_fma_f32 v[8:9], v[36:37], v[180:181], v[8:9] op_sel_hi:[0,1,1]
	ds_read_b128 v[166:169], v29 offset:256
	ds_read_b128 v[170:173], v29 offset:272
	ds_read_b128 v[174:177], v29 offset:288
	ds_read_b128 v[178:181], v29 offset:304
	s_waitcnt vmcnt(62) lgkmcnt(4)
	v_pk_fma_f32 v[22:23], v[38:39], v[182:183], v[22:23] op_sel_hi:[0,1,1]
	v_pk_fma_f32 v[20:21], v[38:39], v[184:185], v[20:21] op_sel_hi:[0,1,1]
	v_pk_fma_f32 v[18:19], v[38:39], v[186:187], v[18:19] op_sel_hi:[0,1,1]
	v_pk_fma_f32 v[16:17], v[38:39], v[188:189], v[16:17] op_sel_hi:[0,1,1]
	v_pk_fma_f32 v[14:15], v[38:39], v[190:191], v[14:15] op_sel_hi:[0,1,1]
	v_pk_fma_f32 v[12:13], v[38:39], v[192:193], v[12:13] op_sel_hi:[0,1,1]
	v_pk_fma_f32 v[10:11], v[38:39], v[194:195], v[10:11] op_sel_hi:[0,1,1]
	v_pk_fma_f32 v[8:9], v[38:39], v[196:197], v[8:9] op_sel_hi:[0,1,1]
	ds_read_b128 v[182:185], v29 offset:384
	ds_read_b128 v[186:189], v29 offset:400
	ds_read_b128 v[190:193], v29 offset:416
	ds_read_b128 v[194:197], v29 offset:432
	s_waitcnt vmcnt(61) lgkmcnt(4)
	v_pk_fma_f32 v[22:23], v[40:41], v[166:167], v[22:23] op_sel_hi:[0,1,1]
	v_pk_fma_f32 v[20:21], v[40:41], v[168:169], v[20:21] op_sel_hi:[0,1,1]
	v_pk_fma_f32 v[18:19], v[40:41], v[170:171], v[18:19] op_sel_hi:[0,1,1]
	v_pk_fma_f32 v[16:17], v[40:41], v[172:173], v[16:17] op_sel_hi:[0,1,1]
	v_pk_fma_f32 v[14:15], v[40:41], v[174:175], v[14:15] op_sel_hi:[0,1,1]
	v_pk_fma_f32 v[12:13], v[40:41], v[176:177], v[12:13] op_sel_hi:[0,1,1]
	v_pk_fma_f32 v[10:11], v[40:41], v[178:179], v[10:11] op_sel_hi:[0,1,1]
	v_pk_fma_f32 v[8:9], v[40:41], v[180:181], v[8:9] op_sel_hi:[0,1,1]
	ds_read_b128 v[166:169], v29 offset:512
	ds_read_b128 v[170:173], v29 offset:528
	ds_read_b128 v[174:177], v29 offset:544
	ds_read_b128 v[178:181], v29 offset:560
	s_waitcnt vmcnt(60) lgkmcnt(4)
	v_pk_fma_f32 v[22:23], v[42:43], v[182:183], v[22:23] op_sel_hi:[0,1,1]
	v_pk_fma_f32 v[20:21], v[42:43], v[184:185], v[20:21] op_sel_hi:[0,1,1]
	v_pk_fma_f32 v[18:19], v[42:43], v[186:187], v[18:19] op_sel_hi:[0,1,1]
	v_pk_fma_f32 v[16:17], v[42:43], v[188:189], v[16:17] op_sel_hi:[0,1,1]
	v_pk_fma_f32 v[14:15], v[42:43], v[190:191], v[14:15] op_sel_hi:[0,1,1]
	v_pk_fma_f32 v[12:13], v[42:43], v[192:193], v[12:13] op_sel_hi:[0,1,1]
	v_pk_fma_f32 v[10:11], v[42:43], v[194:195], v[10:11] op_sel_hi:[0,1,1]
	v_pk_fma_f32 v[8:9], v[42:43], v[196:197], v[8:9] op_sel_hi:[0,1,1]
	ds_read_b128 v[182:185], v29 offset:640
	ds_read_b128 v[186:189], v29 offset:656
	ds_read_b128 v[190:193], v29 offset:672
	ds_read_b128 v[194:197], v29 offset:688
	s_waitcnt vmcnt(59) lgkmcnt(4)
	v_pk_fma_f32 v[22:23], v[44:45], v[166:167], v[22:23] op_sel_hi:[0,1,1]
	v_pk_fma_f32 v[20:21], v[44:45], v[168:169], v[20:21] op_sel_hi:[0,1,1]
	v_pk_fma_f32 v[18:19], v[44:45], v[170:171], v[18:19] op_sel_hi:[0,1,1]
	v_pk_fma_f32 v[16:17], v[44:45], v[172:173], v[16:17] op_sel_hi:[0,1,1]
	v_pk_fma_f32 v[14:15], v[44:45], v[174:175], v[14:15] op_sel_hi:[0,1,1]
	v_pk_fma_f32 v[12:13], v[44:45], v[176:177], v[12:13] op_sel_hi:[0,1,1]
	v_pk_fma_f32 v[10:11], v[44:45], v[178:179], v[10:11] op_sel_hi:[0,1,1]
	v_pk_fma_f32 v[8:9], v[44:45], v[180:181], v[8:9] op_sel_hi:[0,1,1]
	ds_read_b128 v[166:169], v29 offset:768
	ds_read_b128 v[170:173], v29 offset:784
	ds_read_b128 v[174:177], v29 offset:800
	ds_read_b128 v[178:181], v29 offset:816
	s_waitcnt vmcnt(58) lgkmcnt(4)
	v_pk_fma_f32 v[22:23], v[46:47], v[182:183], v[22:23] op_sel_hi:[0,1,1]
	v_pk_fma_f32 v[20:21], v[46:47], v[184:185], v[20:21] op_sel_hi:[0,1,1]
	v_pk_fma_f32 v[18:19], v[46:47], v[186:187], v[18:19] op_sel_hi:[0,1,1]
	v_pk_fma_f32 v[16:17], v[46:47], v[188:189], v[16:17] op_sel_hi:[0,1,1]
	v_pk_fma_f32 v[14:15], v[46:47], v[190:191], v[14:15] op_sel_hi:[0,1,1]
	v_pk_fma_f32 v[12:13], v[46:47], v[192:193], v[12:13] op_sel_hi:[0,1,1]
	v_pk_fma_f32 v[10:11], v[46:47], v[194:195], v[10:11] op_sel_hi:[0,1,1]
	v_pk_fma_f32 v[8:9], v[46:47], v[196:197], v[8:9] op_sel_hi:[0,1,1]
	ds_read_b128 v[182:185], v29 offset:896
	ds_read_b128 v[186:189], v29 offset:912
	ds_read_b128 v[190:193], v29 offset:928
	ds_read_b128 v[194:197], v29 offset:944
	s_waitcnt vmcnt(57) lgkmcnt(4)
	v_pk_fma_f32 v[22:23], v[48:49], v[166:167], v[22:23] op_sel_hi:[0,1,1]
	v_pk_fma_f32 v[20:21], v[48:49], v[168:169], v[20:21] op_sel_hi:[0,1,1]
	v_pk_fma_f32 v[18:19], v[48:49], v[170:171], v[18:19] op_sel_hi:[0,1,1]
	v_pk_fma_f32 v[16:17], v[48:49], v[172:173], v[16:17] op_sel_hi:[0,1,1]
	v_pk_fma_f32 v[14:15], v[48:49], v[174:175], v[14:15] op_sel_hi:[0,1,1]
	v_pk_fma_f32 v[12:13], v[48:49], v[176:177], v[12:13] op_sel_hi:[0,1,1]
	v_pk_fma_f32 v[10:11], v[48:49], v[178:179], v[10:11] op_sel_hi:[0,1,1]
	v_pk_fma_f32 v[8:9], v[48:49], v[180:181], v[8:9] op_sel_hi:[0,1,1]
	ds_read_b128 v[166:169], v29 offset:1024
	ds_read_b128 v[170:173], v29 offset:1040
	ds_read_b128 v[174:177], v29 offset:1056
	ds_read_b128 v[178:181], v29 offset:1072
	s_waitcnt vmcnt(56) lgkmcnt(4)
	v_pk_fma_f32 v[22:23], v[50:51], v[182:183], v[22:23] op_sel_hi:[0,1,1]
	v_pk_fma_f32 v[20:21], v[50:51], v[184:185], v[20:21] op_sel_hi:[0,1,1]
	v_pk_fma_f32 v[18:19], v[50:51], v[186:187], v[18:19] op_sel_hi:[0,1,1]
	v_pk_fma_f32 v[16:17], v[50:51], v[188:189], v[16:17] op_sel_hi:[0,1,1]
	v_pk_fma_f32 v[14:15], v[50:51], v[190:191], v[14:15] op_sel_hi:[0,1,1]
	v_pk_fma_f32 v[12:13], v[50:51], v[192:193], v[12:13] op_sel_hi:[0,1,1]
	v_pk_fma_f32 v[10:11], v[50:51], v[194:195], v[10:11] op_sel_hi:[0,1,1]
	v_pk_fma_f32 v[8:9], v[50:51], v[196:197], v[8:9] op_sel_hi:[0,1,1]
	ds_read_b128 v[182:185], v29 offset:1152
	ds_read_b128 v[186:189], v29 offset:1168
	ds_read_b128 v[190:193], v29 offset:1184
	ds_read_b128 v[194:197], v29 offset:1200
	s_waitcnt vmcnt(55) lgkmcnt(4)
	v_pk_fma_f32 v[22:23], v[52:53], v[166:167], v[22:23] op_sel_hi:[0,1,1]
	v_pk_fma_f32 v[20:21], v[52:53], v[168:169], v[20:21] op_sel_hi:[0,1,1]
	v_pk_fma_f32 v[18:19], v[52:53], v[170:171], v[18:19] op_sel_hi:[0,1,1]
	v_pk_fma_f32 v[16:17], v[52:53], v[172:173], v[16:17] op_sel_hi:[0,1,1]
	v_pk_fma_f32 v[14:15], v[52:53], v[174:175], v[14:15] op_sel_hi:[0,1,1]
	v_pk_fma_f32 v[12:13], v[52:53], v[176:177], v[12:13] op_sel_hi:[0,1,1]
	v_pk_fma_f32 v[10:11], v[52:53], v[178:179], v[10:11] op_sel_hi:[0,1,1]
	v_pk_fma_f32 v[8:9], v[52:53], v[180:181], v[8:9] op_sel_hi:[0,1,1]
	ds_read_b128 v[166:169], v29 offset:1280
	ds_read_b128 v[170:173], v29 offset:1296
	ds_read_b128 v[174:177], v29 offset:1312
	ds_read_b128 v[178:181], v29 offset:1328
	s_waitcnt vmcnt(54) lgkmcnt(4)
	v_pk_fma_f32 v[22:23], v[54:55], v[182:183], v[22:23] op_sel_hi:[0,1,1]
	v_pk_fma_f32 v[20:21], v[54:55], v[184:185], v[20:21] op_sel_hi:[0,1,1]
	v_pk_fma_f32 v[18:19], v[54:55], v[186:187], v[18:19] op_sel_hi:[0,1,1]
	v_pk_fma_f32 v[16:17], v[54:55], v[188:189], v[16:17] op_sel_hi:[0,1,1]
	v_pk_fma_f32 v[14:15], v[54:55], v[190:191], v[14:15] op_sel_hi:[0,1,1]
	v_pk_fma_f32 v[12:13], v[54:55], v[192:193], v[12:13] op_sel_hi:[0,1,1]
	v_pk_fma_f32 v[10:11], v[54:55], v[194:195], v[10:11] op_sel_hi:[0,1,1]
	v_pk_fma_f32 v[8:9], v[54:55], v[196:197], v[8:9] op_sel_hi:[0,1,1]
	ds_read_b128 v[182:185], v29 offset:1408
	ds_read_b128 v[186:189], v29 offset:1424
	ds_read_b128 v[190:193], v29 offset:1440
	ds_read_b128 v[194:197], v29 offset:1456
	s_waitcnt vmcnt(53) lgkmcnt(4)
	v_pk_fma_f32 v[22:23], v[56:57], v[166:167], v[22:23] op_sel_hi:[0,1,1]
	v_pk_fma_f32 v[20:21], v[56:57], v[168:169], v[20:21] op_sel_hi:[0,1,1]
	v_pk_fma_f32 v[18:19], v[56:57], v[170:171], v[18:19] op_sel_hi:[0,1,1]
	v_pk_fma_f32 v[16:17], v[56:57], v[172:173], v[16:17] op_sel_hi:[0,1,1]
	v_pk_fma_f32 v[14:15], v[56:57], v[174:175], v[14:15] op_sel_hi:[0,1,1]
	v_pk_fma_f32 v[12:13], v[56:57], v[176:177], v[12:13] op_sel_hi:[0,1,1]
	v_pk_fma_f32 v[10:11], v[56:57], v[178:179], v[10:11] op_sel_hi:[0,1,1]
	v_pk_fma_f32 v[8:9], v[56:57], v[180:181], v[8:9] op_sel_hi:[0,1,1]
	ds_read_b128 v[166:169], v29 offset:1536
	ds_read_b128 v[170:173], v29 offset:1552
	ds_read_b128 v[174:177], v29 offset:1568
	ds_read_b128 v[178:181], v29 offset:1584
	s_waitcnt vmcnt(52) lgkmcnt(4)
	v_pk_fma_f32 v[22:23], v[58:59], v[182:183], v[22:23] op_sel_hi:[0,1,1]
	v_pk_fma_f32 v[20:21], v[58:59], v[184:185], v[20:21] op_sel_hi:[0,1,1]
	v_pk_fma_f32 v[18:19], v[58:59], v[186:187], v[18:19] op_sel_hi:[0,1,1]
	v_pk_fma_f32 v[16:17], v[58:59], v[188:189], v[16:17] op_sel_hi:[0,1,1]
	v_pk_fma_f32 v[14:15], v[58:59], v[190:191], v[14:15] op_sel_hi:[0,1,1]
	v_pk_fma_f32 v[12:13], v[58:59], v[192:193], v[12:13] op_sel_hi:[0,1,1]
	v_pk_fma_f32 v[10:11], v[58:59], v[194:195], v[10:11] op_sel_hi:[0,1,1]
	v_pk_fma_f32 v[8:9], v[58:59], v[196:197], v[8:9] op_sel_hi:[0,1,1]
	ds_read_b128 v[182:185], v29 offset:1664
	ds_read_b128 v[186:189], v29 offset:1680
	ds_read_b128 v[190:193], v29 offset:1696
	ds_read_b128 v[194:197], v29 offset:1712
	s_waitcnt vmcnt(51) lgkmcnt(4)
	v_pk_fma_f32 v[22:23], v[60:61], v[166:167], v[22:23] op_sel_hi:[0,1,1]
	v_pk_fma_f32 v[20:21], v[60:61], v[168:169], v[20:21] op_sel_hi:[0,1,1]
	v_pk_fma_f32 v[18:19], v[60:61], v[170:171], v[18:19] op_sel_hi:[0,1,1]
	v_pk_fma_f32 v[16:17], v[60:61], v[172:173], v[16:17] op_sel_hi:[0,1,1]
	v_pk_fma_f32 v[14:15], v[60:61], v[174:175], v[14:15] op_sel_hi:[0,1,1]
	v_pk_fma_f32 v[12:13], v[60:61], v[176:177], v[12:13] op_sel_hi:[0,1,1]
	v_pk_fma_f32 v[10:11], v[60:61], v[178:179], v[10:11] op_sel_hi:[0,1,1]
	v_pk_fma_f32 v[8:9], v[60:61], v[180:181], v[8:9] op_sel_hi:[0,1,1]
	ds_read_b128 v[166:169], v29 offset:1792
	ds_read_b128 v[170:173], v29 offset:1808
	ds_read_b128 v[174:177], v29 offset:1824
	ds_read_b128 v[178:181], v29 offset:1840
	s_waitcnt vmcnt(50) lgkmcnt(4)
	v_pk_fma_f32 v[22:23], v[62:63], v[182:183], v[22:23] op_sel_hi:[0,1,1]
	v_pk_fma_f32 v[20:21], v[62:63], v[184:185], v[20:21] op_sel_hi:[0,1,1]
	v_pk_fma_f32 v[18:19], v[62:63], v[186:187], v[18:19] op_sel_hi:[0,1,1]
	v_pk_fma_f32 v[16:17], v[62:63], v[188:189], v[16:17] op_sel_hi:[0,1,1]
	v_pk_fma_f32 v[14:15], v[62:63], v[190:191], v[14:15] op_sel_hi:[0,1,1]
	v_pk_fma_f32 v[12:13], v[62:63], v[192:193], v[12:13] op_sel_hi:[0,1,1]
	v_pk_fma_f32 v[10:11], v[62:63], v[194:195], v[10:11] op_sel_hi:[0,1,1]
	v_pk_fma_f32 v[8:9], v[62:63], v[196:197], v[8:9] op_sel_hi:[0,1,1]
	ds_read_b128 v[182:185], v29 offset:1920
	ds_read_b128 v[186:189], v29 offset:1936
	ds_read_b128 v[190:193], v29 offset:1952
	ds_read_b128 v[194:197], v29 offset:1968
	s_waitcnt vmcnt(49) lgkmcnt(4)
	v_pk_fma_f32 v[22:23], v[64:65], v[166:167], v[22:23] op_sel_hi:[0,1,1]
	v_pk_fma_f32 v[20:21], v[64:65], v[168:169], v[20:21] op_sel_hi:[0,1,1]
	v_pk_fma_f32 v[18:19], v[64:65], v[170:171], v[18:19] op_sel_hi:[0,1,1]
	v_pk_fma_f32 v[16:17], v[64:65], v[172:173], v[16:17] op_sel_hi:[0,1,1]
	v_pk_fma_f32 v[14:15], v[64:65], v[174:175], v[14:15] op_sel_hi:[0,1,1]
	v_pk_fma_f32 v[12:13], v[64:65], v[176:177], v[12:13] op_sel_hi:[0,1,1]
	v_pk_fma_f32 v[10:11], v[64:65], v[178:179], v[10:11] op_sel_hi:[0,1,1]
	v_pk_fma_f32 v[8:9], v[64:65], v[180:181], v[8:9] op_sel_hi:[0,1,1]
	ds_read_b128 v[166:169], v29 offset:2048
	ds_read_b128 v[170:173], v29 offset:2064
	ds_read_b128 v[174:177], v29 offset:2080
	ds_read_b128 v[178:181], v29 offset:2096
	s_waitcnt vmcnt(48) lgkmcnt(4)
	v_pk_fma_f32 v[22:23], v[66:67], v[182:183], v[22:23] op_sel_hi:[0,1,1]
	v_pk_fma_f32 v[20:21], v[66:67], v[184:185], v[20:21] op_sel_hi:[0,1,1]
	v_pk_fma_f32 v[18:19], v[66:67], v[186:187], v[18:19] op_sel_hi:[0,1,1]
	v_pk_fma_f32 v[16:17], v[66:67], v[188:189], v[16:17] op_sel_hi:[0,1,1]
	v_pk_fma_f32 v[14:15], v[66:67], v[190:191], v[14:15] op_sel_hi:[0,1,1]
	v_pk_fma_f32 v[12:13], v[66:67], v[192:193], v[12:13] op_sel_hi:[0,1,1]
	v_pk_fma_f32 v[10:11], v[66:67], v[194:195], v[10:11] op_sel_hi:[0,1,1]
	v_pk_fma_f32 v[8:9], v[66:67], v[196:197], v[8:9] op_sel_hi:[0,1,1]
	ds_read_b128 v[182:185], v29 offset:2176
	ds_read_b128 v[186:189], v29 offset:2192
	ds_read_b128 v[190:193], v29 offset:2208
	ds_read_b128 v[194:197], v29 offset:2224
	s_waitcnt vmcnt(47) lgkmcnt(4)
	v_pk_fma_f32 v[22:23], v[68:69], v[166:167], v[22:23] op_sel_hi:[0,1,1]
	v_pk_fma_f32 v[20:21], v[68:69], v[168:169], v[20:21] op_sel_hi:[0,1,1]
	v_pk_fma_f32 v[18:19], v[68:69], v[170:171], v[18:19] op_sel_hi:[0,1,1]
	v_pk_fma_f32 v[16:17], v[68:69], v[172:173], v[16:17] op_sel_hi:[0,1,1]
	v_pk_fma_f32 v[14:15], v[68:69], v[174:175], v[14:15] op_sel_hi:[0,1,1]
	v_pk_fma_f32 v[12:13], v[68:69], v[176:177], v[12:13] op_sel_hi:[0,1,1]
	v_pk_fma_f32 v[10:11], v[68:69], v[178:179], v[10:11] op_sel_hi:[0,1,1]
	v_pk_fma_f32 v[8:9], v[68:69], v[180:181], v[8:9] op_sel_hi:[0,1,1]
	ds_read_b128 v[166:169], v29 offset:2304
	ds_read_b128 v[170:173], v29 offset:2320
	ds_read_b128 v[174:177], v29 offset:2336
	ds_read_b128 v[178:181], v29 offset:2352
	s_waitcnt vmcnt(46) lgkmcnt(4)
	v_pk_fma_f32 v[22:23], v[70:71], v[182:183], v[22:23] op_sel_hi:[0,1,1]
	v_pk_fma_f32 v[20:21], v[70:71], v[184:185], v[20:21] op_sel_hi:[0,1,1]
	v_pk_fma_f32 v[18:19], v[70:71], v[186:187], v[18:19] op_sel_hi:[0,1,1]
	v_pk_fma_f32 v[16:17], v[70:71], v[188:189], v[16:17] op_sel_hi:[0,1,1]
	v_pk_fma_f32 v[14:15], v[70:71], v[190:191], v[14:15] op_sel_hi:[0,1,1]
	v_pk_fma_f32 v[12:13], v[70:71], v[192:193], v[12:13] op_sel_hi:[0,1,1]
	v_pk_fma_f32 v[10:11], v[70:71], v[194:195], v[10:11] op_sel_hi:[0,1,1]
	v_pk_fma_f32 v[8:9], v[70:71], v[196:197], v[8:9] op_sel_hi:[0,1,1]
	ds_read_b128 v[182:185], v29 offset:2432
	ds_read_b128 v[186:189], v29 offset:2448
	ds_read_b128 v[190:193], v29 offset:2464
	ds_read_b128 v[194:197], v29 offset:2480
	s_waitcnt vmcnt(45) lgkmcnt(4)
	v_pk_fma_f32 v[22:23], v[72:73], v[166:167], v[22:23] op_sel_hi:[0,1,1]
	v_pk_fma_f32 v[20:21], v[72:73], v[168:169], v[20:21] op_sel_hi:[0,1,1]
	v_pk_fma_f32 v[18:19], v[72:73], v[170:171], v[18:19] op_sel_hi:[0,1,1]
	v_pk_fma_f32 v[16:17], v[72:73], v[172:173], v[16:17] op_sel_hi:[0,1,1]
	v_pk_fma_f32 v[14:15], v[72:73], v[174:175], v[14:15] op_sel_hi:[0,1,1]
	v_pk_fma_f32 v[12:13], v[72:73], v[176:177], v[12:13] op_sel_hi:[0,1,1]
	v_pk_fma_f32 v[10:11], v[72:73], v[178:179], v[10:11] op_sel_hi:[0,1,1]
	v_pk_fma_f32 v[8:9], v[72:73], v[180:181], v[8:9] op_sel_hi:[0,1,1]
	ds_read_b128 v[166:169], v29 offset:2560
	ds_read_b128 v[170:173], v29 offset:2576
	ds_read_b128 v[174:177], v29 offset:2592
	ds_read_b128 v[178:181], v29 offset:2608
	s_waitcnt vmcnt(44) lgkmcnt(4)
	v_pk_fma_f32 v[22:23], v[74:75], v[182:183], v[22:23] op_sel_hi:[0,1,1]
	v_pk_fma_f32 v[20:21], v[74:75], v[184:185], v[20:21] op_sel_hi:[0,1,1]
	v_pk_fma_f32 v[18:19], v[74:75], v[186:187], v[18:19] op_sel_hi:[0,1,1]
	v_pk_fma_f32 v[16:17], v[74:75], v[188:189], v[16:17] op_sel_hi:[0,1,1]
	v_pk_fma_f32 v[14:15], v[74:75], v[190:191], v[14:15] op_sel_hi:[0,1,1]
	v_pk_fma_f32 v[12:13], v[74:75], v[192:193], v[12:13] op_sel_hi:[0,1,1]
	v_pk_fma_f32 v[10:11], v[74:75], v[194:195], v[10:11] op_sel_hi:[0,1,1]
	v_pk_fma_f32 v[8:9], v[74:75], v[196:197], v[8:9] op_sel_hi:[0,1,1]
	ds_read_b128 v[182:185], v29 offset:2688
	ds_read_b128 v[186:189], v29 offset:2704
	ds_read_b128 v[190:193], v29 offset:2720
	ds_read_b128 v[194:197], v29 offset:2736
	s_waitcnt vmcnt(43) lgkmcnt(4)
	v_pk_fma_f32 v[22:23], v[76:77], v[166:167], v[22:23] op_sel_hi:[0,1,1]
	v_pk_fma_f32 v[20:21], v[76:77], v[168:169], v[20:21] op_sel_hi:[0,1,1]
	v_pk_fma_f32 v[18:19], v[76:77], v[170:171], v[18:19] op_sel_hi:[0,1,1]
	v_pk_fma_f32 v[16:17], v[76:77], v[172:173], v[16:17] op_sel_hi:[0,1,1]
	v_pk_fma_f32 v[14:15], v[76:77], v[174:175], v[14:15] op_sel_hi:[0,1,1]
	v_pk_fma_f32 v[12:13], v[76:77], v[176:177], v[12:13] op_sel_hi:[0,1,1]
	v_pk_fma_f32 v[10:11], v[76:77], v[178:179], v[10:11] op_sel_hi:[0,1,1]
	v_pk_fma_f32 v[8:9], v[76:77], v[180:181], v[8:9] op_sel_hi:[0,1,1]
	ds_read_b128 v[166:169], v29 offset:2816
	ds_read_b128 v[170:173], v29 offset:2832
	ds_read_b128 v[174:177], v29 offset:2848
	ds_read_b128 v[178:181], v29 offset:2864
	s_waitcnt vmcnt(42) lgkmcnt(4)
	v_pk_fma_f32 v[22:23], v[78:79], v[182:183], v[22:23] op_sel_hi:[0,1,1]
	v_pk_fma_f32 v[20:21], v[78:79], v[184:185], v[20:21] op_sel_hi:[0,1,1]
	v_pk_fma_f32 v[18:19], v[78:79], v[186:187], v[18:19] op_sel_hi:[0,1,1]
	v_pk_fma_f32 v[16:17], v[78:79], v[188:189], v[16:17] op_sel_hi:[0,1,1]
	v_pk_fma_f32 v[14:15], v[78:79], v[190:191], v[14:15] op_sel_hi:[0,1,1]
	v_pk_fma_f32 v[12:13], v[78:79], v[192:193], v[12:13] op_sel_hi:[0,1,1]
	v_pk_fma_f32 v[10:11], v[78:79], v[194:195], v[10:11] op_sel_hi:[0,1,1]
	v_pk_fma_f32 v[8:9], v[78:79], v[196:197], v[8:9] op_sel_hi:[0,1,1]
	ds_read_b128 v[182:185], v29 offset:2944
	ds_read_b128 v[186:189], v29 offset:2960
	ds_read_b128 v[190:193], v29 offset:2976
	ds_read_b128 v[194:197], v29 offset:2992
	s_waitcnt vmcnt(41) lgkmcnt(4)
	v_pk_fma_f32 v[22:23], v[80:81], v[166:167], v[22:23] op_sel_hi:[0,1,1]
	v_pk_fma_f32 v[20:21], v[80:81], v[168:169], v[20:21] op_sel_hi:[0,1,1]
	v_pk_fma_f32 v[18:19], v[80:81], v[170:171], v[18:19] op_sel_hi:[0,1,1]
	v_pk_fma_f32 v[16:17], v[80:81], v[172:173], v[16:17] op_sel_hi:[0,1,1]
	v_pk_fma_f32 v[14:15], v[80:81], v[174:175], v[14:15] op_sel_hi:[0,1,1]
	v_pk_fma_f32 v[12:13], v[80:81], v[176:177], v[12:13] op_sel_hi:[0,1,1]
	v_pk_fma_f32 v[10:11], v[80:81], v[178:179], v[10:11] op_sel_hi:[0,1,1]
	v_pk_fma_f32 v[8:9], v[80:81], v[180:181], v[8:9] op_sel_hi:[0,1,1]
	ds_read_b128 v[166:169], v29 offset:3072
	ds_read_b128 v[170:173], v29 offset:3088
	ds_read_b128 v[174:177], v29 offset:3104
	ds_read_b128 v[178:181], v29 offset:3120
	s_waitcnt vmcnt(40) lgkmcnt(4)
	v_pk_fma_f32 v[22:23], v[82:83], v[182:183], v[22:23] op_sel_hi:[0,1,1]
	v_pk_fma_f32 v[20:21], v[82:83], v[184:185], v[20:21] op_sel_hi:[0,1,1]
	v_pk_fma_f32 v[18:19], v[82:83], v[186:187], v[18:19] op_sel_hi:[0,1,1]
	v_pk_fma_f32 v[16:17], v[82:83], v[188:189], v[16:17] op_sel_hi:[0,1,1]
	v_pk_fma_f32 v[14:15], v[82:83], v[190:191], v[14:15] op_sel_hi:[0,1,1]
	v_pk_fma_f32 v[12:13], v[82:83], v[192:193], v[12:13] op_sel_hi:[0,1,1]
	v_pk_fma_f32 v[10:11], v[82:83], v[194:195], v[10:11] op_sel_hi:[0,1,1]
	v_pk_fma_f32 v[8:9], v[82:83], v[196:197], v[8:9] op_sel_hi:[0,1,1]
	ds_read_b128 v[182:185], v29 offset:3200
	ds_read_b128 v[186:189], v29 offset:3216
	ds_read_b128 v[190:193], v29 offset:3232
	ds_read_b128 v[194:197], v29 offset:3248
	s_waitcnt vmcnt(39) lgkmcnt(4)
	v_pk_fma_f32 v[22:23], v[84:85], v[166:167], v[22:23] op_sel_hi:[0,1,1]
	v_pk_fma_f32 v[20:21], v[84:85], v[168:169], v[20:21] op_sel_hi:[0,1,1]
	v_pk_fma_f32 v[18:19], v[84:85], v[170:171], v[18:19] op_sel_hi:[0,1,1]
	v_pk_fma_f32 v[16:17], v[84:85], v[172:173], v[16:17] op_sel_hi:[0,1,1]
	v_pk_fma_f32 v[14:15], v[84:85], v[174:175], v[14:15] op_sel_hi:[0,1,1]
	v_pk_fma_f32 v[12:13], v[84:85], v[176:177], v[12:13] op_sel_hi:[0,1,1]
	v_pk_fma_f32 v[10:11], v[84:85], v[178:179], v[10:11] op_sel_hi:[0,1,1]
	v_pk_fma_f32 v[8:9], v[84:85], v[180:181], v[8:9] op_sel_hi:[0,1,1]
	ds_read_b128 v[166:169], v29 offset:3328
	ds_read_b128 v[170:173], v29 offset:3344
	ds_read_b128 v[174:177], v29 offset:3360
	ds_read_b128 v[178:181], v29 offset:3376
	s_waitcnt vmcnt(38) lgkmcnt(4)
	v_pk_fma_f32 v[22:23], v[86:87], v[182:183], v[22:23] op_sel_hi:[0,1,1]
	v_pk_fma_f32 v[20:21], v[86:87], v[184:185], v[20:21] op_sel_hi:[0,1,1]
	v_pk_fma_f32 v[18:19], v[86:87], v[186:187], v[18:19] op_sel_hi:[0,1,1]
	v_pk_fma_f32 v[16:17], v[86:87], v[188:189], v[16:17] op_sel_hi:[0,1,1]
	v_pk_fma_f32 v[14:15], v[86:87], v[190:191], v[14:15] op_sel_hi:[0,1,1]
	v_pk_fma_f32 v[12:13], v[86:87], v[192:193], v[12:13] op_sel_hi:[0,1,1]
	v_pk_fma_f32 v[10:11], v[86:87], v[194:195], v[10:11] op_sel_hi:[0,1,1]
	v_pk_fma_f32 v[8:9], v[86:87], v[196:197], v[8:9] op_sel_hi:[0,1,1]
	ds_read_b128 v[182:185], v29 offset:3456
	ds_read_b128 v[186:189], v29 offset:3472
	ds_read_b128 v[190:193], v29 offset:3488
	ds_read_b128 v[194:197], v29 offset:3504
	s_waitcnt vmcnt(37) lgkmcnt(4)
	v_pk_fma_f32 v[22:23], v[88:89], v[166:167], v[22:23] op_sel_hi:[0,1,1]
	v_pk_fma_f32 v[20:21], v[88:89], v[168:169], v[20:21] op_sel_hi:[0,1,1]
	v_pk_fma_f32 v[18:19], v[88:89], v[170:171], v[18:19] op_sel_hi:[0,1,1]
	v_pk_fma_f32 v[16:17], v[88:89], v[172:173], v[16:17] op_sel_hi:[0,1,1]
	v_pk_fma_f32 v[14:15], v[88:89], v[174:175], v[14:15] op_sel_hi:[0,1,1]
	v_pk_fma_f32 v[12:13], v[88:89], v[176:177], v[12:13] op_sel_hi:[0,1,1]
	v_pk_fma_f32 v[10:11], v[88:89], v[178:179], v[10:11] op_sel_hi:[0,1,1]
	v_pk_fma_f32 v[8:9], v[88:89], v[180:181], v[8:9] op_sel_hi:[0,1,1]
	ds_read_b128 v[166:169], v29 offset:3584
	ds_read_b128 v[170:173], v29 offset:3600
	ds_read_b128 v[174:177], v29 offset:3616
	ds_read_b128 v[178:181], v29 offset:3632
	s_waitcnt vmcnt(36) lgkmcnt(4)
	v_pk_fma_f32 v[22:23], v[90:91], v[182:183], v[22:23] op_sel_hi:[0,1,1]
	v_pk_fma_f32 v[20:21], v[90:91], v[184:185], v[20:21] op_sel_hi:[0,1,1]
	v_pk_fma_f32 v[18:19], v[90:91], v[186:187], v[18:19] op_sel_hi:[0,1,1]
	v_pk_fma_f32 v[16:17], v[90:91], v[188:189], v[16:17] op_sel_hi:[0,1,1]
	v_pk_fma_f32 v[14:15], v[90:91], v[190:191], v[14:15] op_sel_hi:[0,1,1]
	v_pk_fma_f32 v[12:13], v[90:91], v[192:193], v[12:13] op_sel_hi:[0,1,1]
	v_pk_fma_f32 v[10:11], v[90:91], v[194:195], v[10:11] op_sel_hi:[0,1,1]
	v_pk_fma_f32 v[8:9], v[90:91], v[196:197], v[8:9] op_sel_hi:[0,1,1]
	ds_read_b128 v[182:185], v29 offset:3712
	ds_read_b128 v[186:189], v29 offset:3728
	ds_read_b128 v[190:193], v29 offset:3744
	ds_read_b128 v[194:197], v29 offset:3760
	s_waitcnt vmcnt(35) lgkmcnt(4)
	v_pk_fma_f32 v[22:23], v[92:93], v[166:167], v[22:23] op_sel_hi:[0,1,1]
	v_pk_fma_f32 v[20:21], v[92:93], v[168:169], v[20:21] op_sel_hi:[0,1,1]
	v_pk_fma_f32 v[18:19], v[92:93], v[170:171], v[18:19] op_sel_hi:[0,1,1]
	v_pk_fma_f32 v[16:17], v[92:93], v[172:173], v[16:17] op_sel_hi:[0,1,1]
	v_pk_fma_f32 v[14:15], v[92:93], v[174:175], v[14:15] op_sel_hi:[0,1,1]
	v_pk_fma_f32 v[12:13], v[92:93], v[176:177], v[12:13] op_sel_hi:[0,1,1]
	v_pk_fma_f32 v[10:11], v[92:93], v[178:179], v[10:11] op_sel_hi:[0,1,1]
	v_pk_fma_f32 v[8:9], v[92:93], v[180:181], v[8:9] op_sel_hi:[0,1,1]
	ds_read_b128 v[166:169], v29 offset:3840
	ds_read_b128 v[170:173], v29 offset:3856
	ds_read_b128 v[174:177], v29 offset:3872
	ds_read_b128 v[178:181], v29 offset:3888
	s_waitcnt vmcnt(34) lgkmcnt(4)
	v_pk_fma_f32 v[22:23], v[94:95], v[182:183], v[22:23] op_sel_hi:[0,1,1]
	v_pk_fma_f32 v[20:21], v[94:95], v[184:185], v[20:21] op_sel_hi:[0,1,1]
	v_pk_fma_f32 v[18:19], v[94:95], v[186:187], v[18:19] op_sel_hi:[0,1,1]
	v_pk_fma_f32 v[16:17], v[94:95], v[188:189], v[16:17] op_sel_hi:[0,1,1]
	v_pk_fma_f32 v[14:15], v[94:95], v[190:191], v[14:15] op_sel_hi:[0,1,1]
	v_pk_fma_f32 v[12:13], v[94:95], v[192:193], v[12:13] op_sel_hi:[0,1,1]
	v_pk_fma_f32 v[10:11], v[94:95], v[194:195], v[10:11] op_sel_hi:[0,1,1]
	v_pk_fma_f32 v[8:9], v[94:95], v[196:197], v[8:9] op_sel_hi:[0,1,1]
	ds_read_b128 v[182:185], v29 offset:3968
	ds_read_b128 v[186:189], v29 offset:3984
	ds_read_b128 v[190:193], v29 offset:4000
	ds_read_b128 v[194:197], v29 offset:4016
	s_waitcnt vmcnt(33) lgkmcnt(4)
	v_pk_fma_f32 v[22:23], v[96:97], v[166:167], v[22:23] op_sel_hi:[0,1,1]
	v_pk_fma_f32 v[20:21], v[96:97], v[168:169], v[20:21] op_sel_hi:[0,1,1]
	v_pk_fma_f32 v[18:19], v[96:97], v[170:171], v[18:19] op_sel_hi:[0,1,1]
	v_pk_fma_f32 v[16:17], v[96:97], v[172:173], v[16:17] op_sel_hi:[0,1,1]
	v_pk_fma_f32 v[14:15], v[96:97], v[174:175], v[14:15] op_sel_hi:[0,1,1]
	v_pk_fma_f32 v[12:13], v[96:97], v[176:177], v[12:13] op_sel_hi:[0,1,1]
	v_pk_fma_f32 v[10:11], v[96:97], v[178:179], v[10:11] op_sel_hi:[0,1,1]
	v_pk_fma_f32 v[8:9], v[96:97], v[180:181], v[8:9] op_sel_hi:[0,1,1]
	ds_read_b128 v[166:169], v29 offset:4096
	ds_read_b128 v[170:173], v29 offset:4112
	ds_read_b128 v[174:177], v29 offset:4128
	ds_read_b128 v[178:181], v29 offset:4144
	s_waitcnt vmcnt(32) lgkmcnt(4)
	v_pk_fma_f32 v[22:23], v[98:99], v[182:183], v[22:23] op_sel_hi:[0,1,1]
	v_pk_fma_f32 v[20:21], v[98:99], v[184:185], v[20:21] op_sel_hi:[0,1,1]
	v_pk_fma_f32 v[18:19], v[98:99], v[186:187], v[18:19] op_sel_hi:[0,1,1]
	v_pk_fma_f32 v[16:17], v[98:99], v[188:189], v[16:17] op_sel_hi:[0,1,1]
	v_pk_fma_f32 v[14:15], v[98:99], v[190:191], v[14:15] op_sel_hi:[0,1,1]
	v_pk_fma_f32 v[12:13], v[98:99], v[192:193], v[12:13] op_sel_hi:[0,1,1]
	v_pk_fma_f32 v[10:11], v[98:99], v[194:195], v[10:11] op_sel_hi:[0,1,1]
	v_pk_fma_f32 v[8:9], v[98:99], v[196:197], v[8:9] op_sel_hi:[0,1,1]
	ds_read_b128 v[182:185], v29 offset:4224
	ds_read_b128 v[186:189], v29 offset:4240
	ds_read_b128 v[190:193], v29 offset:4256
	ds_read_b128 v[194:197], v29 offset:4272
	s_waitcnt vmcnt(31) lgkmcnt(4)
	v_pk_fma_f32 v[22:23], v[100:101], v[166:167], v[22:23] op_sel_hi:[0,1,1]
	v_pk_fma_f32 v[20:21], v[100:101], v[168:169], v[20:21] op_sel_hi:[0,1,1]
	v_pk_fma_f32 v[18:19], v[100:101], v[170:171], v[18:19] op_sel_hi:[0,1,1]
	v_pk_fma_f32 v[16:17], v[100:101], v[172:173], v[16:17] op_sel_hi:[0,1,1]
	v_pk_fma_f32 v[14:15], v[100:101], v[174:175], v[14:15] op_sel_hi:[0,1,1]
	v_pk_fma_f32 v[12:13], v[100:101], v[176:177], v[12:13] op_sel_hi:[0,1,1]
	v_pk_fma_f32 v[10:11], v[100:101], v[178:179], v[10:11] op_sel_hi:[0,1,1]
	v_pk_fma_f32 v[8:9], v[100:101], v[180:181], v[8:9] op_sel_hi:[0,1,1]
	ds_read_b128 v[166:169], v29 offset:4352
	ds_read_b128 v[170:173], v29 offset:4368
	ds_read_b128 v[174:177], v29 offset:4384
	ds_read_b128 v[178:181], v29 offset:4400
	s_waitcnt vmcnt(30) lgkmcnt(4)
	v_pk_fma_f32 v[22:23], v[102:103], v[182:183], v[22:23] op_sel_hi:[0,1,1]
	v_pk_fma_f32 v[20:21], v[102:103], v[184:185], v[20:21] op_sel_hi:[0,1,1]
	v_pk_fma_f32 v[18:19], v[102:103], v[186:187], v[18:19] op_sel_hi:[0,1,1]
	v_pk_fma_f32 v[16:17], v[102:103], v[188:189], v[16:17] op_sel_hi:[0,1,1]
	v_pk_fma_f32 v[14:15], v[102:103], v[190:191], v[14:15] op_sel_hi:[0,1,1]
	v_pk_fma_f32 v[12:13], v[102:103], v[192:193], v[12:13] op_sel_hi:[0,1,1]
	v_pk_fma_f32 v[10:11], v[102:103], v[194:195], v[10:11] op_sel_hi:[0,1,1]
	v_pk_fma_f32 v[8:9], v[102:103], v[196:197], v[8:9] op_sel_hi:[0,1,1]
	ds_read_b128 v[182:185], v29 offset:4480
	ds_read_b128 v[186:189], v29 offset:4496
	ds_read_b128 v[190:193], v29 offset:4512
	ds_read_b128 v[194:197], v29 offset:4528
	s_waitcnt vmcnt(29) lgkmcnt(4)
	v_pk_fma_f32 v[22:23], v[104:105], v[166:167], v[22:23] op_sel_hi:[0,1,1]
	v_pk_fma_f32 v[20:21], v[104:105], v[168:169], v[20:21] op_sel_hi:[0,1,1]
	v_pk_fma_f32 v[18:19], v[104:105], v[170:171], v[18:19] op_sel_hi:[0,1,1]
	v_pk_fma_f32 v[16:17], v[104:105], v[172:173], v[16:17] op_sel_hi:[0,1,1]
	v_pk_fma_f32 v[14:15], v[104:105], v[174:175], v[14:15] op_sel_hi:[0,1,1]
	v_pk_fma_f32 v[12:13], v[104:105], v[176:177], v[12:13] op_sel_hi:[0,1,1]
	v_pk_fma_f32 v[10:11], v[104:105], v[178:179], v[10:11] op_sel_hi:[0,1,1]
	v_pk_fma_f32 v[8:9], v[104:105], v[180:181], v[8:9] op_sel_hi:[0,1,1]
	ds_read_b128 v[166:169], v29 offset:4608
	ds_read_b128 v[170:173], v29 offset:4624
	ds_read_b128 v[174:177], v29 offset:4640
	ds_read_b128 v[178:181], v29 offset:4656
	s_waitcnt vmcnt(28) lgkmcnt(4)
	v_pk_fma_f32 v[22:23], v[106:107], v[182:183], v[22:23] op_sel_hi:[0,1,1]
	v_pk_fma_f32 v[20:21], v[106:107], v[184:185], v[20:21] op_sel_hi:[0,1,1]
	v_pk_fma_f32 v[18:19], v[106:107], v[186:187], v[18:19] op_sel_hi:[0,1,1]
	v_pk_fma_f32 v[16:17], v[106:107], v[188:189], v[16:17] op_sel_hi:[0,1,1]
	v_pk_fma_f32 v[14:15], v[106:107], v[190:191], v[14:15] op_sel_hi:[0,1,1]
	v_pk_fma_f32 v[12:13], v[106:107], v[192:193], v[12:13] op_sel_hi:[0,1,1]
	v_pk_fma_f32 v[10:11], v[106:107], v[194:195], v[10:11] op_sel_hi:[0,1,1]
	v_pk_fma_f32 v[8:9], v[106:107], v[196:197], v[8:9] op_sel_hi:[0,1,1]
	ds_read_b128 v[182:185], v29 offset:4736
	ds_read_b128 v[186:189], v29 offset:4752
	ds_read_b128 v[190:193], v29 offset:4768
	ds_read_b128 v[194:197], v29 offset:4784
	s_waitcnt vmcnt(27) lgkmcnt(4)
	v_pk_fma_f32 v[22:23], v[108:109], v[166:167], v[22:23] op_sel_hi:[0,1,1]
	v_pk_fma_f32 v[20:21], v[108:109], v[168:169], v[20:21] op_sel_hi:[0,1,1]
	v_pk_fma_f32 v[18:19], v[108:109], v[170:171], v[18:19] op_sel_hi:[0,1,1]
	v_pk_fma_f32 v[16:17], v[108:109], v[172:173], v[16:17] op_sel_hi:[0,1,1]
	v_pk_fma_f32 v[14:15], v[108:109], v[174:175], v[14:15] op_sel_hi:[0,1,1]
	v_pk_fma_f32 v[12:13], v[108:109], v[176:177], v[12:13] op_sel_hi:[0,1,1]
	v_pk_fma_f32 v[10:11], v[108:109], v[178:179], v[10:11] op_sel_hi:[0,1,1]
	v_pk_fma_f32 v[8:9], v[108:109], v[180:181], v[8:9] op_sel_hi:[0,1,1]
	ds_read_b128 v[166:169], v29 offset:4864
	ds_read_b128 v[170:173], v29 offset:4880
	ds_read_b128 v[174:177], v29 offset:4896
	ds_read_b128 v[178:181], v29 offset:4912
	s_waitcnt vmcnt(26) lgkmcnt(4)
	v_pk_fma_f32 v[22:23], v[110:111], v[182:183], v[22:23] op_sel_hi:[0,1,1]
	v_pk_fma_f32 v[20:21], v[110:111], v[184:185], v[20:21] op_sel_hi:[0,1,1]
	v_pk_fma_f32 v[18:19], v[110:111], v[186:187], v[18:19] op_sel_hi:[0,1,1]
	v_pk_fma_f32 v[16:17], v[110:111], v[188:189], v[16:17] op_sel_hi:[0,1,1]
	v_pk_fma_f32 v[14:15], v[110:111], v[190:191], v[14:15] op_sel_hi:[0,1,1]
	v_pk_fma_f32 v[12:13], v[110:111], v[192:193], v[12:13] op_sel_hi:[0,1,1]
	v_pk_fma_f32 v[10:11], v[110:111], v[194:195], v[10:11] op_sel_hi:[0,1,1]
	v_pk_fma_f32 v[8:9], v[110:111], v[196:197], v[8:9] op_sel_hi:[0,1,1]
	ds_read_b128 v[182:185], v29 offset:4992
	ds_read_b128 v[186:189], v29 offset:5008
	ds_read_b128 v[190:193], v29 offset:5024
	ds_read_b128 v[194:197], v29 offset:5040
	s_waitcnt vmcnt(25) lgkmcnt(4)
	v_pk_fma_f32 v[22:23], v[112:113], v[166:167], v[22:23] op_sel_hi:[0,1,1]
	v_pk_fma_f32 v[20:21], v[112:113], v[168:169], v[20:21] op_sel_hi:[0,1,1]
	v_pk_fma_f32 v[18:19], v[112:113], v[170:171], v[18:19] op_sel_hi:[0,1,1]
	v_pk_fma_f32 v[16:17], v[112:113], v[172:173], v[16:17] op_sel_hi:[0,1,1]
	v_pk_fma_f32 v[14:15], v[112:113], v[174:175], v[14:15] op_sel_hi:[0,1,1]
	v_pk_fma_f32 v[12:13], v[112:113], v[176:177], v[12:13] op_sel_hi:[0,1,1]
	v_pk_fma_f32 v[10:11], v[112:113], v[178:179], v[10:11] op_sel_hi:[0,1,1]
	v_pk_fma_f32 v[8:9], v[112:113], v[180:181], v[8:9] op_sel_hi:[0,1,1]
	ds_read_b128 v[166:169], v29 offset:5120
	ds_read_b128 v[170:173], v29 offset:5136
	ds_read_b128 v[174:177], v29 offset:5152
	ds_read_b128 v[178:181], v29 offset:5168
	s_waitcnt vmcnt(24) lgkmcnt(4)
	v_pk_fma_f32 v[22:23], v[114:115], v[182:183], v[22:23] op_sel_hi:[0,1,1]
	v_pk_fma_f32 v[20:21], v[114:115], v[184:185], v[20:21] op_sel_hi:[0,1,1]
	v_pk_fma_f32 v[18:19], v[114:115], v[186:187], v[18:19] op_sel_hi:[0,1,1]
	v_pk_fma_f32 v[16:17], v[114:115], v[188:189], v[16:17] op_sel_hi:[0,1,1]
	v_pk_fma_f32 v[14:15], v[114:115], v[190:191], v[14:15] op_sel_hi:[0,1,1]
	v_pk_fma_f32 v[12:13], v[114:115], v[192:193], v[12:13] op_sel_hi:[0,1,1]
	v_pk_fma_f32 v[10:11], v[114:115], v[194:195], v[10:11] op_sel_hi:[0,1,1]
	v_pk_fma_f32 v[8:9], v[114:115], v[196:197], v[8:9] op_sel_hi:[0,1,1]
	ds_read_b128 v[182:185], v29 offset:5248
	ds_read_b128 v[186:189], v29 offset:5264
	ds_read_b128 v[190:193], v29 offset:5280
	ds_read_b128 v[194:197], v29 offset:5296
	s_waitcnt vmcnt(23) lgkmcnt(4)
	v_pk_fma_f32 v[22:23], v[116:117], v[166:167], v[22:23] op_sel_hi:[0,1,1]
	v_pk_fma_f32 v[20:21], v[116:117], v[168:169], v[20:21] op_sel_hi:[0,1,1]
	v_pk_fma_f32 v[18:19], v[116:117], v[170:171], v[18:19] op_sel_hi:[0,1,1]
	v_pk_fma_f32 v[16:17], v[116:117], v[172:173], v[16:17] op_sel_hi:[0,1,1]
	v_pk_fma_f32 v[14:15], v[116:117], v[174:175], v[14:15] op_sel_hi:[0,1,1]
	v_pk_fma_f32 v[12:13], v[116:117], v[176:177], v[12:13] op_sel_hi:[0,1,1]
	v_pk_fma_f32 v[10:11], v[116:117], v[178:179], v[10:11] op_sel_hi:[0,1,1]
	v_pk_fma_f32 v[8:9], v[116:117], v[180:181], v[8:9] op_sel_hi:[0,1,1]
	ds_read_b128 v[166:169], v29 offset:5376
	ds_read_b128 v[170:173], v29 offset:5392
	ds_read_b128 v[174:177], v29 offset:5408
	ds_read_b128 v[178:181], v29 offset:5424
	s_waitcnt vmcnt(22) lgkmcnt(4)
	v_pk_fma_f32 v[22:23], v[118:119], v[182:183], v[22:23] op_sel_hi:[0,1,1]
	v_pk_fma_f32 v[20:21], v[118:119], v[184:185], v[20:21] op_sel_hi:[0,1,1]
	v_pk_fma_f32 v[18:19], v[118:119], v[186:187], v[18:19] op_sel_hi:[0,1,1]
	v_pk_fma_f32 v[16:17], v[118:119], v[188:189], v[16:17] op_sel_hi:[0,1,1]
	v_pk_fma_f32 v[14:15], v[118:119], v[190:191], v[14:15] op_sel_hi:[0,1,1]
	v_pk_fma_f32 v[12:13], v[118:119], v[192:193], v[12:13] op_sel_hi:[0,1,1]
	v_pk_fma_f32 v[10:11], v[118:119], v[194:195], v[10:11] op_sel_hi:[0,1,1]
	v_pk_fma_f32 v[8:9], v[118:119], v[196:197], v[8:9] op_sel_hi:[0,1,1]
	ds_read_b128 v[182:185], v29 offset:5504
	ds_read_b128 v[186:189], v29 offset:5520
	ds_read_b128 v[190:193], v29 offset:5536
	ds_read_b128 v[194:197], v29 offset:5552
	s_waitcnt vmcnt(21) lgkmcnt(4)
	v_pk_fma_f32 v[22:23], v[120:121], v[166:167], v[22:23] op_sel_hi:[0,1,1]
	v_pk_fma_f32 v[20:21], v[120:121], v[168:169], v[20:21] op_sel_hi:[0,1,1]
	v_pk_fma_f32 v[18:19], v[120:121], v[170:171], v[18:19] op_sel_hi:[0,1,1]
	v_pk_fma_f32 v[16:17], v[120:121], v[172:173], v[16:17] op_sel_hi:[0,1,1]
	v_pk_fma_f32 v[14:15], v[120:121], v[174:175], v[14:15] op_sel_hi:[0,1,1]
	v_pk_fma_f32 v[12:13], v[120:121], v[176:177], v[12:13] op_sel_hi:[0,1,1]
	v_pk_fma_f32 v[10:11], v[120:121], v[178:179], v[10:11] op_sel_hi:[0,1,1]
	v_pk_fma_f32 v[8:9], v[120:121], v[180:181], v[8:9] op_sel_hi:[0,1,1]
	ds_read_b128 v[166:169], v29 offset:5632
	ds_read_b128 v[170:173], v29 offset:5648
	ds_read_b128 v[174:177], v29 offset:5664
	ds_read_b128 v[178:181], v29 offset:5680
	s_waitcnt vmcnt(20) lgkmcnt(4)
	v_pk_fma_f32 v[22:23], v[122:123], v[182:183], v[22:23] op_sel_hi:[0,1,1]
	v_pk_fma_f32 v[20:21], v[122:123], v[184:185], v[20:21] op_sel_hi:[0,1,1]
	v_pk_fma_f32 v[18:19], v[122:123], v[186:187], v[18:19] op_sel_hi:[0,1,1]
	v_pk_fma_f32 v[16:17], v[122:123], v[188:189], v[16:17] op_sel_hi:[0,1,1]
	v_pk_fma_f32 v[14:15], v[122:123], v[190:191], v[14:15] op_sel_hi:[0,1,1]
	v_pk_fma_f32 v[12:13], v[122:123], v[192:193], v[12:13] op_sel_hi:[0,1,1]
	v_pk_fma_f32 v[10:11], v[122:123], v[194:195], v[10:11] op_sel_hi:[0,1,1]
	v_pk_fma_f32 v[8:9], v[122:123], v[196:197], v[8:9] op_sel_hi:[0,1,1]
	ds_read_b128 v[182:185], v29 offset:5760
	ds_read_b128 v[186:189], v29 offset:5776
	ds_read_b128 v[190:193], v29 offset:5792
	ds_read_b128 v[194:197], v29 offset:5808
	s_waitcnt vmcnt(19) lgkmcnt(4)
	v_pk_fma_f32 v[22:23], v[124:125], v[166:167], v[22:23] op_sel_hi:[0,1,1]
	v_pk_fma_f32 v[20:21], v[124:125], v[168:169], v[20:21] op_sel_hi:[0,1,1]
	v_pk_fma_f32 v[18:19], v[124:125], v[170:171], v[18:19] op_sel_hi:[0,1,1]
	v_pk_fma_f32 v[16:17], v[124:125], v[172:173], v[16:17] op_sel_hi:[0,1,1]
	v_pk_fma_f32 v[14:15], v[124:125], v[174:175], v[14:15] op_sel_hi:[0,1,1]
	v_pk_fma_f32 v[12:13], v[124:125], v[176:177], v[12:13] op_sel_hi:[0,1,1]
	v_pk_fma_f32 v[10:11], v[124:125], v[178:179], v[10:11] op_sel_hi:[0,1,1]
	v_pk_fma_f32 v[8:9], v[124:125], v[180:181], v[8:9] op_sel_hi:[0,1,1]
	ds_read_b128 v[166:169], v29 offset:5888
	ds_read_b128 v[170:173], v29 offset:5904
	ds_read_b128 v[174:177], v29 offset:5920
	ds_read_b128 v[178:181], v29 offset:5936
	s_waitcnt vmcnt(18) lgkmcnt(4)
	v_pk_fma_f32 v[22:23], v[126:127], v[182:183], v[22:23] op_sel_hi:[0,1,1]
	v_pk_fma_f32 v[20:21], v[126:127], v[184:185], v[20:21] op_sel_hi:[0,1,1]
	v_pk_fma_f32 v[18:19], v[126:127], v[186:187], v[18:19] op_sel_hi:[0,1,1]
	v_pk_fma_f32 v[16:17], v[126:127], v[188:189], v[16:17] op_sel_hi:[0,1,1]
	v_pk_fma_f32 v[14:15], v[126:127], v[190:191], v[14:15] op_sel_hi:[0,1,1]
	v_pk_fma_f32 v[12:13], v[126:127], v[192:193], v[12:13] op_sel_hi:[0,1,1]
	v_pk_fma_f32 v[10:11], v[126:127], v[194:195], v[10:11] op_sel_hi:[0,1,1]
	v_pk_fma_f32 v[8:9], v[126:127], v[196:197], v[8:9] op_sel_hi:[0,1,1]
	ds_read_b128 v[182:185], v29 offset:6016
	ds_read_b128 v[186:189], v29 offset:6032
	ds_read_b128 v[190:193], v29 offset:6048
	ds_read_b128 v[194:197], v29 offset:6064
	s_waitcnt vmcnt(17) lgkmcnt(4)
	v_pk_fma_f32 v[22:23], v[128:129], v[166:167], v[22:23] op_sel_hi:[0,1,1]
	v_pk_fma_f32 v[20:21], v[128:129], v[168:169], v[20:21] op_sel_hi:[0,1,1]
	v_pk_fma_f32 v[18:19], v[128:129], v[170:171], v[18:19] op_sel_hi:[0,1,1]
	v_pk_fma_f32 v[16:17], v[128:129], v[172:173], v[16:17] op_sel_hi:[0,1,1]
	v_pk_fma_f32 v[14:15], v[128:129], v[174:175], v[14:15] op_sel_hi:[0,1,1]
	v_pk_fma_f32 v[12:13], v[128:129], v[176:177], v[12:13] op_sel_hi:[0,1,1]
	v_pk_fma_f32 v[10:11], v[128:129], v[178:179], v[10:11] op_sel_hi:[0,1,1]
	v_pk_fma_f32 v[8:9], v[128:129], v[180:181], v[8:9] op_sel_hi:[0,1,1]
	ds_read_b128 v[166:169], v29 offset:6144
	ds_read_b128 v[170:173], v29 offset:6160
	ds_read_b128 v[174:177], v29 offset:6176
	ds_read_b128 v[178:181], v29 offset:6192
	s_waitcnt vmcnt(16) lgkmcnt(4)
	v_pk_fma_f32 v[22:23], v[130:131], v[182:183], v[22:23] op_sel_hi:[0,1,1]
	v_pk_fma_f32 v[20:21], v[130:131], v[184:185], v[20:21] op_sel_hi:[0,1,1]
	v_pk_fma_f32 v[18:19], v[130:131], v[186:187], v[18:19] op_sel_hi:[0,1,1]
	v_pk_fma_f32 v[16:17], v[130:131], v[188:189], v[16:17] op_sel_hi:[0,1,1]
	v_pk_fma_f32 v[14:15], v[130:131], v[190:191], v[14:15] op_sel_hi:[0,1,1]
	v_pk_fma_f32 v[12:13], v[130:131], v[192:193], v[12:13] op_sel_hi:[0,1,1]
	v_pk_fma_f32 v[10:11], v[130:131], v[194:195], v[10:11] op_sel_hi:[0,1,1]
	v_pk_fma_f32 v[8:9], v[130:131], v[196:197], v[8:9] op_sel_hi:[0,1,1]
	ds_read_b128 v[182:185], v29 offset:6272
	ds_read_b128 v[186:189], v29 offset:6288
	ds_read_b128 v[190:193], v29 offset:6304
	ds_read_b128 v[194:197], v29 offset:6320
	s_waitcnt vmcnt(15) lgkmcnt(4)
	v_pk_fma_f32 v[22:23], v[132:133], v[166:167], v[22:23] op_sel_hi:[0,1,1]
	v_pk_fma_f32 v[20:21], v[132:133], v[168:169], v[20:21] op_sel_hi:[0,1,1]
	v_pk_fma_f32 v[18:19], v[132:133], v[170:171], v[18:19] op_sel_hi:[0,1,1]
	v_pk_fma_f32 v[16:17], v[132:133], v[172:173], v[16:17] op_sel_hi:[0,1,1]
	v_pk_fma_f32 v[14:15], v[132:133], v[174:175], v[14:15] op_sel_hi:[0,1,1]
	v_pk_fma_f32 v[12:13], v[132:133], v[176:177], v[12:13] op_sel_hi:[0,1,1]
	v_pk_fma_f32 v[10:11], v[132:133], v[178:179], v[10:11] op_sel_hi:[0,1,1]
	v_pk_fma_f32 v[8:9], v[132:133], v[180:181], v[8:9] op_sel_hi:[0,1,1]
	ds_read_b128 v[166:169], v29 offset:6400
	ds_read_b128 v[170:173], v29 offset:6416
	ds_read_b128 v[174:177], v29 offset:6432
	ds_read_b128 v[178:181], v29 offset:6448
	s_waitcnt vmcnt(14) lgkmcnt(4)
	v_pk_fma_f32 v[22:23], v[134:135], v[182:183], v[22:23] op_sel_hi:[0,1,1]
	v_pk_fma_f32 v[20:21], v[134:135], v[184:185], v[20:21] op_sel_hi:[0,1,1]
	v_pk_fma_f32 v[18:19], v[134:135], v[186:187], v[18:19] op_sel_hi:[0,1,1]
	v_pk_fma_f32 v[16:17], v[134:135], v[188:189], v[16:17] op_sel_hi:[0,1,1]
	v_pk_fma_f32 v[14:15], v[134:135], v[190:191], v[14:15] op_sel_hi:[0,1,1]
	v_pk_fma_f32 v[12:13], v[134:135], v[192:193], v[12:13] op_sel_hi:[0,1,1]
	v_pk_fma_f32 v[10:11], v[134:135], v[194:195], v[10:11] op_sel_hi:[0,1,1]
	v_pk_fma_f32 v[8:9], v[134:135], v[196:197], v[8:9] op_sel_hi:[0,1,1]
	ds_read_b128 v[182:185], v29 offset:6528
	ds_read_b128 v[186:189], v29 offset:6544
	ds_read_b128 v[190:193], v29 offset:6560
	ds_read_b128 v[194:197], v29 offset:6576
	s_waitcnt vmcnt(13) lgkmcnt(4)
	v_pk_fma_f32 v[22:23], v[136:137], v[166:167], v[22:23] op_sel_hi:[0,1,1]
	v_pk_fma_f32 v[20:21], v[136:137], v[168:169], v[20:21] op_sel_hi:[0,1,1]
	v_pk_fma_f32 v[18:19], v[136:137], v[170:171], v[18:19] op_sel_hi:[0,1,1]
	v_pk_fma_f32 v[16:17], v[136:137], v[172:173], v[16:17] op_sel_hi:[0,1,1]
	v_pk_fma_f32 v[14:15], v[136:137], v[174:175], v[14:15] op_sel_hi:[0,1,1]
	v_pk_fma_f32 v[12:13], v[136:137], v[176:177], v[12:13] op_sel_hi:[0,1,1]
	v_pk_fma_f32 v[10:11], v[136:137], v[178:179], v[10:11] op_sel_hi:[0,1,1]
	v_pk_fma_f32 v[8:9], v[136:137], v[180:181], v[8:9] op_sel_hi:[0,1,1]
	ds_read_b128 v[166:169], v29 offset:6656
	ds_read_b128 v[170:173], v29 offset:6672
	ds_read_b128 v[174:177], v29 offset:6688
	ds_read_b128 v[178:181], v29 offset:6704
	s_waitcnt vmcnt(12) lgkmcnt(4)
	v_pk_fma_f32 v[22:23], v[138:139], v[182:183], v[22:23] op_sel_hi:[0,1,1]
	v_pk_fma_f32 v[20:21], v[138:139], v[184:185], v[20:21] op_sel_hi:[0,1,1]
	v_pk_fma_f32 v[18:19], v[138:139], v[186:187], v[18:19] op_sel_hi:[0,1,1]
	v_pk_fma_f32 v[16:17], v[138:139], v[188:189], v[16:17] op_sel_hi:[0,1,1]
	v_pk_fma_f32 v[14:15], v[138:139], v[190:191], v[14:15] op_sel_hi:[0,1,1]
	v_pk_fma_f32 v[12:13], v[138:139], v[192:193], v[12:13] op_sel_hi:[0,1,1]
	v_pk_fma_f32 v[10:11], v[138:139], v[194:195], v[10:11] op_sel_hi:[0,1,1]
	v_pk_fma_f32 v[8:9], v[138:139], v[196:197], v[8:9] op_sel_hi:[0,1,1]
	ds_read_b128 v[182:185], v29 offset:6784
	ds_read_b128 v[186:189], v29 offset:6800
	ds_read_b128 v[190:193], v29 offset:6816
	ds_read_b128 v[194:197], v29 offset:6832
	s_waitcnt vmcnt(11) lgkmcnt(4)
	v_pk_fma_f32 v[22:23], v[140:141], v[166:167], v[22:23] op_sel_hi:[0,1,1]
	v_pk_fma_f32 v[20:21], v[140:141], v[168:169], v[20:21] op_sel_hi:[0,1,1]
	v_pk_fma_f32 v[18:19], v[140:141], v[170:171], v[18:19] op_sel_hi:[0,1,1]
	v_pk_fma_f32 v[16:17], v[140:141], v[172:173], v[16:17] op_sel_hi:[0,1,1]
	v_pk_fma_f32 v[14:15], v[140:141], v[174:175], v[14:15] op_sel_hi:[0,1,1]
	v_pk_fma_f32 v[12:13], v[140:141], v[176:177], v[12:13] op_sel_hi:[0,1,1]
	v_pk_fma_f32 v[10:11], v[140:141], v[178:179], v[10:11] op_sel_hi:[0,1,1]
	v_pk_fma_f32 v[8:9], v[140:141], v[180:181], v[8:9] op_sel_hi:[0,1,1]
	ds_read_b128 v[166:169], v29 offset:6912
	ds_read_b128 v[170:173], v29 offset:6928
	ds_read_b128 v[174:177], v29 offset:6944
	ds_read_b128 v[178:181], v29 offset:6960
	s_waitcnt vmcnt(10) lgkmcnt(4)
	v_pk_fma_f32 v[22:23], v[142:143], v[182:183], v[22:23] op_sel_hi:[0,1,1]
	v_pk_fma_f32 v[20:21], v[142:143], v[184:185], v[20:21] op_sel_hi:[0,1,1]
	v_pk_fma_f32 v[18:19], v[142:143], v[186:187], v[18:19] op_sel_hi:[0,1,1]
	v_pk_fma_f32 v[16:17], v[142:143], v[188:189], v[16:17] op_sel_hi:[0,1,1]
	v_pk_fma_f32 v[14:15], v[142:143], v[190:191], v[14:15] op_sel_hi:[0,1,1]
	v_pk_fma_f32 v[12:13], v[142:143], v[192:193], v[12:13] op_sel_hi:[0,1,1]
	v_pk_fma_f32 v[10:11], v[142:143], v[194:195], v[10:11] op_sel_hi:[0,1,1]
	v_pk_fma_f32 v[8:9], v[142:143], v[196:197], v[8:9] op_sel_hi:[0,1,1]
	ds_read_b128 v[182:185], v29 offset:7040
	ds_read_b128 v[186:189], v29 offset:7056
	ds_read_b128 v[190:193], v29 offset:7072
	ds_read_b128 v[194:197], v29 offset:7088
	s_waitcnt vmcnt(9) lgkmcnt(4)
	v_pk_fma_f32 v[22:23], v[144:145], v[166:167], v[22:23] op_sel_hi:[0,1,1]
	v_pk_fma_f32 v[20:21], v[144:145], v[168:169], v[20:21] op_sel_hi:[0,1,1]
	v_pk_fma_f32 v[18:19], v[144:145], v[170:171], v[18:19] op_sel_hi:[0,1,1]
	v_pk_fma_f32 v[16:17], v[144:145], v[172:173], v[16:17] op_sel_hi:[0,1,1]
	v_pk_fma_f32 v[14:15], v[144:145], v[174:175], v[14:15] op_sel_hi:[0,1,1]
	v_pk_fma_f32 v[12:13], v[144:145], v[176:177], v[12:13] op_sel_hi:[0,1,1]
	v_pk_fma_f32 v[10:11], v[144:145], v[178:179], v[10:11] op_sel_hi:[0,1,1]
	v_pk_fma_f32 v[8:9], v[144:145], v[180:181], v[8:9] op_sel_hi:[0,1,1]
	ds_read_b128 v[166:169], v29 offset:7168
	ds_read_b128 v[170:173], v29 offset:7184
	ds_read_b128 v[174:177], v29 offset:7200
	ds_read_b128 v[178:181], v29 offset:7216
	s_waitcnt vmcnt(8) lgkmcnt(4)
	v_pk_fma_f32 v[22:23], v[146:147], v[182:183], v[22:23] op_sel_hi:[0,1,1]
	v_pk_fma_f32 v[20:21], v[146:147], v[184:185], v[20:21] op_sel_hi:[0,1,1]
	v_pk_fma_f32 v[18:19], v[146:147], v[186:187], v[18:19] op_sel_hi:[0,1,1]
	v_pk_fma_f32 v[16:17], v[146:147], v[188:189], v[16:17] op_sel_hi:[0,1,1]
	v_pk_fma_f32 v[14:15], v[146:147], v[190:191], v[14:15] op_sel_hi:[0,1,1]
	v_pk_fma_f32 v[12:13], v[146:147], v[192:193], v[12:13] op_sel_hi:[0,1,1]
	v_pk_fma_f32 v[10:11], v[146:147], v[194:195], v[10:11] op_sel_hi:[0,1,1]
	v_pk_fma_f32 v[8:9], v[146:147], v[196:197], v[8:9] op_sel_hi:[0,1,1]
	ds_read_b128 v[182:185], v29 offset:7296
	ds_read_b128 v[186:189], v29 offset:7312
	ds_read_b128 v[190:193], v29 offset:7328
	ds_read_b128 v[194:197], v29 offset:7344
	s_waitcnt vmcnt(7) lgkmcnt(4)
	v_pk_fma_f32 v[22:23], v[148:149], v[166:167], v[22:23] op_sel_hi:[0,1,1]
	v_pk_fma_f32 v[20:21], v[148:149], v[168:169], v[20:21] op_sel_hi:[0,1,1]
	v_pk_fma_f32 v[18:19], v[148:149], v[170:171], v[18:19] op_sel_hi:[0,1,1]
	v_pk_fma_f32 v[16:17], v[148:149], v[172:173], v[16:17] op_sel_hi:[0,1,1]
	v_pk_fma_f32 v[14:15], v[148:149], v[174:175], v[14:15] op_sel_hi:[0,1,1]
	v_pk_fma_f32 v[12:13], v[148:149], v[176:177], v[12:13] op_sel_hi:[0,1,1]
	v_pk_fma_f32 v[10:11], v[148:149], v[178:179], v[10:11] op_sel_hi:[0,1,1]
	v_pk_fma_f32 v[8:9], v[148:149], v[180:181], v[8:9] op_sel_hi:[0,1,1]
	ds_read_b128 v[166:169], v29 offset:7424
	ds_read_b128 v[170:173], v29 offset:7440
	ds_read_b128 v[174:177], v29 offset:7456
	ds_read_b128 v[178:181], v29 offset:7472
	s_waitcnt vmcnt(6) lgkmcnt(4)
	v_pk_fma_f32 v[22:23], v[150:151], v[182:183], v[22:23] op_sel_hi:[0,1,1]
	v_pk_fma_f32 v[20:21], v[150:151], v[184:185], v[20:21] op_sel_hi:[0,1,1]
	v_pk_fma_f32 v[18:19], v[150:151], v[186:187], v[18:19] op_sel_hi:[0,1,1]
	v_pk_fma_f32 v[16:17], v[150:151], v[188:189], v[16:17] op_sel_hi:[0,1,1]
	v_pk_fma_f32 v[14:15], v[150:151], v[190:191], v[14:15] op_sel_hi:[0,1,1]
	v_pk_fma_f32 v[12:13], v[150:151], v[192:193], v[12:13] op_sel_hi:[0,1,1]
	v_pk_fma_f32 v[10:11], v[150:151], v[194:195], v[10:11] op_sel_hi:[0,1,1]
	v_pk_fma_f32 v[8:9], v[150:151], v[196:197], v[8:9] op_sel_hi:[0,1,1]
	ds_read_b128 v[182:185], v29 offset:7552
	ds_read_b128 v[186:189], v29 offset:7568
	ds_read_b128 v[190:193], v29 offset:7584
	ds_read_b128 v[194:197], v29 offset:7600
	s_waitcnt vmcnt(5) lgkmcnt(4)
	v_pk_fma_f32 v[22:23], v[152:153], v[166:167], v[22:23] op_sel_hi:[0,1,1]
	v_pk_fma_f32 v[20:21], v[152:153], v[168:169], v[20:21] op_sel_hi:[0,1,1]
	v_pk_fma_f32 v[18:19], v[152:153], v[170:171], v[18:19] op_sel_hi:[0,1,1]
	v_pk_fma_f32 v[16:17], v[152:153], v[172:173], v[16:17] op_sel_hi:[0,1,1]
	v_pk_fma_f32 v[14:15], v[152:153], v[174:175], v[14:15] op_sel_hi:[0,1,1]
	v_pk_fma_f32 v[12:13], v[152:153], v[176:177], v[12:13] op_sel_hi:[0,1,1]
	v_pk_fma_f32 v[10:11], v[152:153], v[178:179], v[10:11] op_sel_hi:[0,1,1]
	v_pk_fma_f32 v[8:9], v[152:153], v[180:181], v[8:9] op_sel_hi:[0,1,1]
	ds_read_b128 v[166:169], v29 offset:7680
	ds_read_b128 v[170:173], v29 offset:7696
	ds_read_b128 v[174:177], v29 offset:7712
	ds_read_b128 v[178:181], v29 offset:7728
	s_waitcnt vmcnt(4) lgkmcnt(4)
	v_pk_fma_f32 v[22:23], v[154:155], v[182:183], v[22:23] op_sel_hi:[0,1,1]
	v_pk_fma_f32 v[20:21], v[154:155], v[184:185], v[20:21] op_sel_hi:[0,1,1]
	v_pk_fma_f32 v[18:19], v[154:155], v[186:187], v[18:19] op_sel_hi:[0,1,1]
	v_pk_fma_f32 v[16:17], v[154:155], v[188:189], v[16:17] op_sel_hi:[0,1,1]
	v_pk_fma_f32 v[14:15], v[154:155], v[190:191], v[14:15] op_sel_hi:[0,1,1]
	v_pk_fma_f32 v[12:13], v[154:155], v[192:193], v[12:13] op_sel_hi:[0,1,1]
	v_pk_fma_f32 v[10:11], v[154:155], v[194:195], v[10:11] op_sel_hi:[0,1,1]
	v_pk_fma_f32 v[8:9], v[154:155], v[196:197], v[8:9] op_sel_hi:[0,1,1]
	ds_read_b128 v[182:185], v29 offset:7808
	ds_read_b128 v[186:189], v29 offset:7824
	ds_read_b128 v[190:193], v29 offset:7840
	ds_read_b128 v[194:197], v29 offset:7856
	s_waitcnt vmcnt(3) lgkmcnt(4)
	v_pk_fma_f32 v[22:23], v[156:157], v[166:167], v[22:23] op_sel_hi:[0,1,1]
	v_pk_fma_f32 v[20:21], v[156:157], v[168:169], v[20:21] op_sel_hi:[0,1,1]
	v_pk_fma_f32 v[18:19], v[156:157], v[170:171], v[18:19] op_sel_hi:[0,1,1]
	v_pk_fma_f32 v[16:17], v[156:157], v[172:173], v[16:17] op_sel_hi:[0,1,1]
	v_pk_fma_f32 v[14:15], v[156:157], v[174:175], v[14:15] op_sel_hi:[0,1,1]
	v_pk_fma_f32 v[12:13], v[156:157], v[176:177], v[12:13] op_sel_hi:[0,1,1]
	v_pk_fma_f32 v[10:11], v[156:157], v[178:179], v[10:11] op_sel_hi:[0,1,1]
	v_pk_fma_f32 v[8:9], v[156:157], v[180:181], v[8:9] op_sel_hi:[0,1,1]
	ds_read_b128 v[166:169], v29 offset:7936
	ds_read_b128 v[170:173], v29 offset:7952
	ds_read_b128 v[174:177], v29 offset:7968
	ds_read_b128 v[178:181], v29 offset:7984
	s_waitcnt vmcnt(2) lgkmcnt(4)
	v_pk_fma_f32 v[22:23], v[158:159], v[182:183], v[22:23] op_sel_hi:[0,1,1]
	v_pk_fma_f32 v[20:21], v[158:159], v[184:185], v[20:21] op_sel_hi:[0,1,1]
	v_pk_fma_f32 v[18:19], v[158:159], v[186:187], v[18:19] op_sel_hi:[0,1,1]
	v_pk_fma_f32 v[16:17], v[158:159], v[188:189], v[16:17] op_sel_hi:[0,1,1]
	v_pk_fma_f32 v[14:15], v[158:159], v[190:191], v[14:15] op_sel_hi:[0,1,1]
	v_pk_fma_f32 v[12:13], v[158:159], v[192:193], v[12:13] op_sel_hi:[0,1,1]
	v_pk_fma_f32 v[10:11], v[158:159], v[194:195], v[10:11] op_sel_hi:[0,1,1]
	v_pk_fma_f32 v[8:9], v[158:159], v[196:197], v[8:9] op_sel_hi:[0,1,1]
	ds_read_b128 v[182:185], v29 offset:8064
	ds_read_b128 v[186:189], v29 offset:8080
	ds_read_b128 v[190:193], v29 offset:8096
	ds_read_b128 v[194:197], v29 offset:8112
	s_waitcnt vmcnt(1) lgkmcnt(4)
	v_pk_fma_f32 v[22:23], v[160:161], v[166:167], v[22:23] op_sel_hi:[0,1,1]
	v_pk_fma_f32 v[20:21], v[160:161], v[168:169], v[20:21] op_sel_hi:[0,1,1]
	v_pk_fma_f32 v[18:19], v[160:161], v[170:171], v[18:19] op_sel_hi:[0,1,1]
	v_pk_fma_f32 v[16:17], v[160:161], v[172:173], v[16:17] op_sel_hi:[0,1,1]
	v_pk_fma_f32 v[14:15], v[160:161], v[174:175], v[14:15] op_sel_hi:[0,1,1]
	v_pk_fma_f32 v[12:13], v[160:161], v[176:177], v[12:13] op_sel_hi:[0,1,1]
	v_pk_fma_f32 v[10:11], v[160:161], v[178:179], v[10:11] op_sel_hi:[0,1,1]
	v_pk_fma_f32 v[8:9], v[160:161], v[180:181], v[8:9] op_sel_hi:[0,1,1]
	s_waitcnt vmcnt(0) lgkmcnt(0)
	v_pk_fma_f32 v[22:23], v[162:163], v[182:183], v[22:23] op_sel_hi:[0,1,1]
	v_pk_fma_f32 v[20:21], v[162:163], v[184:185], v[20:21] op_sel_hi:[0,1,1]
	v_pk_fma_f32 v[18:19], v[162:163], v[186:187], v[18:19] op_sel_hi:[0,1,1]
	v_pk_fma_f32 v[16:17], v[162:163], v[188:189], v[16:17] op_sel_hi:[0,1,1]
	v_pk_fma_f32 v[14:15], v[162:163], v[190:191], v[14:15] op_sel_hi:[0,1,1]
	v_pk_fma_f32 v[12:13], v[162:163], v[192:193], v[12:13] op_sel_hi:[0,1,1]
	v_pk_fma_f32 v[10:11], v[162:163], v[194:195], v[10:11] op_sel_hi:[0,1,1]
	v_pk_fma_f32 v[8:9], v[162:163], v[196:197], v[8:9] op_sel_hi:[0,1,1]
	v_mov_b32_e32 v6, v22
	s_nop 1
	v_permlane32_swap_b32_e32 v22, v6
	s_and_saveexec_b64 s[2:3], vcc
	v_add_f32_e32 v6, v22, v6
	ds_write_b32 v26, v6
	s_or_b64 exec, exec, s[2:3]
	v_mov_b32_e32 v6, v23
	s_nop 1
	v_permlane32_swap_b32_e32 v23, v6
	s_and_saveexec_b64 s[2:3], vcc
	v_add_f32_e32 v6, v23, v6
	ds_write_b32 v26, v6 offset:128
	s_or_b64 exec, exec, s[2:3]
	v_mov_b32_e32 v6, v20
	s_nop 1
	v_permlane32_swap_b32_e32 v20, v6
	s_and_saveexec_b64 s[2:3], vcc
	v_add_f32_e32 v6, v20, v6
	ds_write_b32 v26, v6 offset:256
	s_or_b64 exec, exec, s[2:3]
	v_mov_b32_e32 v6, v21
	s_nop 1
	v_permlane32_swap_b32_e32 v21, v6
	s_and_saveexec_b64 s[2:3], vcc
	v_add_f32_e32 v6, v21, v6
	ds_write_b32 v26, v6 offset:384
	s_or_b64 exec, exec, s[2:3]
	v_mov_b32_e32 v6, v18
	s_nop 1
	v_permlane32_swap_b32_e32 v18, v6
	s_and_saveexec_b64 s[2:3], vcc
	v_add_f32_e32 v6, v18, v6
	ds_write_b32 v26, v6 offset:512
	s_or_b64 exec, exec, s[2:3]
	v_mov_b32_e32 v6, v19
	s_nop 1
	v_permlane32_swap_b32_e32 v19, v6
	s_and_saveexec_b64 s[2:3], vcc
	v_add_f32_e32 v6, v19, v6
	ds_write_b32 v26, v6 offset:640
	s_or_b64 exec, exec, s[2:3]
	v_mov_b32_e32 v6, v16
	s_nop 1
	v_permlane32_swap_b32_e32 v16, v6
	s_and_saveexec_b64 s[2:3], vcc
	v_add_f32_e32 v6, v16, v6
	ds_write_b32 v26, v6 offset:768
	s_or_b64 exec, exec, s[2:3]
	v_mov_b32_e32 v6, v17
	s_nop 1
	v_permlane32_swap_b32_e32 v17, v6
	s_and_saveexec_b64 s[2:3], vcc
	v_add_f32_e32 v6, v17, v6
	ds_write_b32 v26, v6 offset:896
	s_or_b64 exec, exec, s[2:3]
	v_mov_b32_e32 v6, v14
	s_nop 1
	v_permlane32_swap_b32_e32 v14, v6
	s_and_saveexec_b64 s[2:3], vcc
	v_add_f32_e32 v6, v14, v6
	ds_write_b32 v26, v6 offset:1024
	s_or_b64 exec, exec, s[2:3]
	v_mov_b32_e32 v6, v15
	s_nop 1
	v_permlane32_swap_b32_e32 v15, v6
	s_and_saveexec_b64 s[2:3], vcc
	v_add_f32_e32 v6, v15, v6
	ds_write_b32 v26, v6 offset:1152
	s_or_b64 exec, exec, s[2:3]
	v_mov_b32_e32 v6, v12
	s_nop 1
	v_permlane32_swap_b32_e32 v12, v6
	s_and_saveexec_b64 s[2:3], vcc
	v_add_f32_e32 v6, v12, v6
	ds_write_b32 v26, v6 offset:1280
	s_or_b64 exec, exec, s[2:3]
	v_mov_b32_e32 v6, v13
	s_nop 1
	v_permlane32_swap_b32_e32 v13, v6
	s_and_saveexec_b64 s[2:3], vcc
	v_add_f32_e32 v6, v13, v6
	ds_write_b32 v26, v6 offset:1408
	s_or_b64 exec, exec, s[2:3]
	v_mov_b32_e32 v6, v10
	s_nop 1
	v_permlane32_swap_b32_e32 v10, v6
	s_and_saveexec_b64 s[2:3], vcc
	v_add_f32_e32 v6, v10, v6
	ds_write_b32 v26, v6 offset:1536
	s_or_b64 exec, exec, s[2:3]
	v_mov_b32_e32 v6, v11
	s_nop 1
	v_permlane32_swap_b32_e32 v11, v6
	s_and_saveexec_b64 s[2:3], vcc
	v_add_f32_e32 v6, v11, v6
	ds_write_b32 v26, v6 offset:1664
	s_or_b64 exec, exec, s[2:3]
	v_mov_b32_e32 v6, v8
	s_nop 1
	v_permlane32_swap_b32_e32 v8, v6
	s_and_saveexec_b64 s[2:3], vcc
	v_add_f32_e32 v6, v8, v6
	ds_write_b32 v26, v6 offset:1792
	s_or_b64 exec, exec, s[2:3]
	v_mov_b32_e32 v6, v9
	s_nop 1
	v_permlane32_swap_b32_e32 v9, v6
	s_and_saveexec_b64 s[2:3], vcc
	s_cbranch_execz .LBB0_1567
	v_add_f32_e32 v6, v9, v6
	ds_write_b32 v26, v6 offset:1920
	s_branch .LBB0_1567
